# k20 + lever 1 in the in-proj epilogue: rotary blocks of row groups 1-3 no longer drain the previous row groups' stores (counted vmcnt instead of vmcnt(0))
# speedup vs baseline: 1.0089x; 1.0089x over previous
.LBB0_577:
	v_and_b32_e32 v186, 64, v235
	v_xor_b32_e32 v0, 16, v235
	v_add_u32_e32 v186, 64, v186
	v_cmp_lt_i32_e32 vcc, v0, v186
	s_nop 1
	v_cndmask_b32_e32 v0, v235, v0, vcc
	v_lshlrev_b32_e32 v0, 2, v0
	ds_bpermute_b32 v188, v0, v178
	ds_bpermute_b32 v189, v0, v179
	ds_bpermute_b32 v186, v0, v180
	ds_bpermute_b32 v187, v0, v181
	ds_bpermute_b32 v190, v0, v182
	ds_bpermute_b32 v191, v0, v183
	ds_bpermute_b32 v192, v0, v184
	ds_bpermute_b32 v0, v0, v185
	s_and_saveexec_b64 s[4:5], s[8:9]
	s_cbranch_execz .LBB0_579
	s_waitcnt lgkmcnt(0)
	v_mul_f32_e32 v195, v224, v0
	v_mov_b32_e32 v196, v185
	s_waitcnt vmcnt(9)
	v_mov_b32_e32 v197, v137
	v_mov_b32_e32 v194, v133
	v_mul_f32_e32 v192, v224, v192
	v_pk_mul_f32 v[194:195], v[196:197], v[194:195]
	v_pk_mul_f32 v[180:181], v[180:181], v[144:145]
	v_pk_mul_f32 v[178:179], v[178:179], v[142:143]
	v_pk_mul_f32 v[188:189], v[224:225], v[188:189] op_sel_hi:[0,1]
	v_pk_mul_f32 v[182:183], v[182:183], v[130:131]
	v_pk_mul_f32 v[190:191], v[224:225], v[190:191] op_sel_hi:[0,1]
	v_mul_f32_e32 v184, v184, v132
	v_mul_f32_e32 v192, v136, v192
	v_pk_mul_f32 v[186:187], v[224:225], v[186:187] op_sel_hi:[0,1]
	v_mov_b32_e32 v185, v194
	v_mov_b32_e32 v193, v195
	v_pk_fma_f32 v[178:179], v[138:139], v[188:189], v[178:179]
	v_pk_fma_f32 v[180:181], v[140:141], v[186:187], v[180:181]
	v_pk_fma_f32 v[182:183], v[134:135], v[190:191], v[182:183]
	v_pk_add_f32 v[184:185], v[184:185], v[192:193]

.LBB0_617:
	v_and_b32_e32 v178, 64, v235
	v_xor_b32_e32 v0, 16, v235
	v_add_u32_e32 v178, 64, v178
	v_cmp_lt_i32_e32 vcc, v0, v178
	s_nop 1
	v_cndmask_b32_e32 v0, v235, v0, vcc
	v_lshlrev_b32_e32 v0, 2, v0
	ds_bpermute_b32 v180, v0, v170
	ds_bpermute_b32 v181, v0, v171
	ds_bpermute_b32 v178, v0, v172
	ds_bpermute_b32 v179, v0, v173
	ds_bpermute_b32 v182, v0, v174
	ds_bpermute_b32 v183, v0, v175
	ds_bpermute_b32 v184, v0, v176
	ds_bpermute_b32 v0, v0, v177
	s_and_saveexec_b64 s[4:5], s[8:9]
	s_cbranch_execz .LBB0_619
	s_waitcnt lgkmcnt(0)
	v_mul_f32_e32 v187, v224, v0
	v_mov_b32_e32 v188, v177
	s_waitcnt vmcnt(6)
	v_mov_b32_e32 v189, v113
	v_mov_b32_e32 v186, v109
	v_mul_f32_e32 v184, v224, v184
	v_pk_mul_f32 v[186:187], v[188:189], v[186:187]
	v_pk_mul_f32 v[172:173], v[172:173], v[120:121]
	v_pk_mul_f32 v[170:171], v[170:171], v[118:119]
	v_pk_mul_f32 v[180:181], v[224:225], v[180:181] op_sel_hi:[0,1]
	v_pk_mul_f32 v[174:175], v[174:175], v[106:107]
	v_pk_mul_f32 v[182:183], v[224:225], v[182:183] op_sel_hi:[0,1]
	v_mul_f32_e32 v176, v176, v108
	v_mul_f32_e32 v184, v112, v184
	v_pk_mul_f32 v[178:179], v[224:225], v[178:179] op_sel_hi:[0,1]
	v_mov_b32_e32 v177, v186
	v_mov_b32_e32 v185, v187
	v_pk_fma_f32 v[170:171], v[114:115], v[180:181], v[170:171]
	v_pk_fma_f32 v[172:173], v[116:117], v[178:179], v[172:173]
	v_pk_fma_f32 v[174:175], v[110:111], v[182:183], v[174:175]
	v_pk_add_f32 v[176:177], v[176:177], v[184:185]

.LBB0_657:
	v_and_b32_e32 v170, 64, v235
	v_xor_b32_e32 v0, 16, v235
	v_add_u32_e32 v170, 64, v170
	v_cmp_lt_i32_e32 vcc, v0, v170
	s_nop 1
	v_cndmask_b32_e32 v0, v235, v0, vcc
	v_lshlrev_b32_e32 v0, 2, v0
	ds_bpermute_b32 v172, v0, v146
	ds_bpermute_b32 v173, v0, v147
	ds_bpermute_b32 v170, v0, v148
	ds_bpermute_b32 v171, v0, v149
	ds_bpermute_b32 v174, v0, v166
	ds_bpermute_b32 v175, v0, v167
	ds_bpermute_b32 v176, v0, v168
	ds_bpermute_b32 v0, v0, v169
	s_and_saveexec_b64 s[4:5], s[8:9]
	s_cbranch_execz .LBB0_659
	s_waitcnt lgkmcnt(0)
	v_mul_f32_e32 v179, v224, v0
	v_mov_b32_e32 v180, v169
	s_waitcnt vmcnt(3)
	v_mov_b32_e32 v181, v89
	v_mov_b32_e32 v178, v85
	v_mul_f32_e32 v176, v224, v176
	v_pk_mul_f32 v[178:179], v[180:181], v[178:179]
	v_pk_mul_f32 v[148:149], v[148:149], v[96:97]
	v_pk_mul_f32 v[146:147], v[146:147], v[94:95]
	v_pk_mul_f32 v[172:173], v[224:225], v[172:173] op_sel_hi:[0,1]
	v_pk_mul_f32 v[166:167], v[166:167], v[82:83]
	v_pk_mul_f32 v[174:175], v[224:225], v[174:175] op_sel_hi:[0,1]
	v_mul_f32_e32 v168, v168, v84
	v_mul_f32_e32 v176, v88, v176
	v_pk_mul_f32 v[170:171], v[224:225], v[170:171] op_sel_hi:[0,1]
	v_mov_b32_e32 v169, v178
	v_mov_b32_e32 v177, v179
	v_pk_fma_f32 v[146:147], v[90:91], v[172:173], v[146:147]
	v_pk_fma_f32 v[148:149], v[92:93], v[170:171], v[148:149]
	v_pk_fma_f32 v[166:167], v[86:87], v[174:175], v[166:167]
	v_pk_add_f32 v[168:169], v[168:169], v[176:177]

.LBB0_954:
	v_and_b32_e32 v58, 64, v235
	v_xor_b32_e32 v0, 16, v235
	v_add_u32_e32 v58, 64, v58
	v_cmp_lt_i32_e32 vcc, v0, v58
	s_nop 1
	v_cndmask_b32_e32 v0, v235, v0, vcc
	v_lshlrev_b32_e32 v0, 2, v0
	ds_bpermute_b32 v60, v0, v50
	ds_bpermute_b32 v61, v0, v51
	ds_bpermute_b32 v58, v0, v52
	ds_bpermute_b32 v59, v0, v53
	ds_bpermute_b32 v62, v0, v54
	ds_bpermute_b32 v63, v0, v55
	ds_bpermute_b32 v64, v0, v56
	ds_bpermute_b32 v0, v0, v57
	s_and_saveexec_b64 s[4:5], s[8:9]
	s_cbranch_execz .LBB0_956
	s_waitcnt lgkmcnt(0)
	v_mul_f32_e32 v131, v140, v0
	v_mov_b32_e32 v132, v57
	s_waitcnt vmcnt(9)
	v_mov_b32_e32 v133, v105
	v_mov_b32_e32 v130, v101
	v_mul_f32_e32 v64, v140, v64
	v_pk_mul_f32 v[130:131], v[132:133], v[130:131]
	v_pk_mul_f32 v[52:53], v[52:53], v[112:113]
	v_pk_mul_f32 v[50:51], v[50:51], v[110:111]
	v_pk_mul_f32 v[60:61], v[140:141], v[60:61] op_sel_hi:[0,1]
	v_pk_mul_f32 v[54:55], v[54:55], v[98:99]
	v_pk_mul_f32 v[62:63], v[140:141], v[62:63] op_sel_hi:[0,1]
	v_mul_f32_e32 v56, v56, v100
	v_mul_f32_e32 v64, v104, v64
	v_pk_mul_f32 v[58:59], v[140:141], v[58:59] op_sel_hi:[0,1]
	v_mov_b32_e32 v57, v130
	v_mov_b32_e32 v65, v131
	v_pk_fma_f32 v[50:51], v[106:107], v[60:61], v[50:51]
	v_pk_fma_f32 v[52:53], v[108:109], v[58:59], v[52:53]
	v_pk_fma_f32 v[54:55], v[102:103], v[62:63], v[54:55]
	v_pk_add_f32 v[56:57], v[56:57], v[64:65]

.LBB0_994:
	v_and_b32_e32 v50, 64, v235
	v_xor_b32_e32 v0, 16, v235
	v_add_u32_e32 v50, 64, v50
	v_cmp_lt_i32_e32 vcc, v0, v50
	s_nop 1
	v_cndmask_b32_e32 v0, v235, v0, vcc
	v_lshlrev_b32_e32 v0, 2, v0
	ds_bpermute_b32 v52, v0, v42
	ds_bpermute_b32 v53, v0, v43
	ds_bpermute_b32 v50, v0, v44
	ds_bpermute_b32 v51, v0, v45
	ds_bpermute_b32 v54, v0, v46
	ds_bpermute_b32 v55, v0, v47
	ds_bpermute_b32 v56, v0, v48
	ds_bpermute_b32 v0, v0, v49
	s_and_saveexec_b64 s[4:5], s[8:9]
	s_cbranch_execz .LBB0_996
	s_waitcnt lgkmcnt(0)
	v_mul_f32_e32 v59, v140, v0
	v_mov_b32_e32 v60, v49
	s_waitcnt vmcnt(6)
	v_mov_b32_e32 v61, v89
	v_mov_b32_e32 v58, v85
	v_mul_f32_e32 v56, v140, v56
	v_pk_mul_f32 v[58:59], v[60:61], v[58:59]
	v_pk_mul_f32 v[44:45], v[44:45], v[96:97]
	v_pk_mul_f32 v[42:43], v[42:43], v[94:95]
	v_pk_mul_f32 v[52:53], v[140:141], v[52:53] op_sel_hi:[0,1]
	v_pk_mul_f32 v[46:47], v[46:47], v[82:83]
	v_pk_mul_f32 v[54:55], v[140:141], v[54:55] op_sel_hi:[0,1]
	v_mul_f32_e32 v48, v48, v84
	v_mul_f32_e32 v56, v88, v56
	v_pk_mul_f32 v[50:51], v[140:141], v[50:51] op_sel_hi:[0,1]
	v_mov_b32_e32 v49, v58
	v_mov_b32_e32 v57, v59
	v_pk_fma_f32 v[42:43], v[90:91], v[52:53], v[42:43]
	v_pk_fma_f32 v[44:45], v[92:93], v[50:51], v[44:45]
	v_pk_fma_f32 v[46:47], v[86:87], v[54:55], v[46:47]
	v_pk_add_f32 v[48:49], v[48:49], v[56:57]

.LBB0_1034:
	v_and_b32_e32 v42, 64, v235
	v_xor_b32_e32 v0, 16, v235
	v_add_u32_e32 v42, 64, v42
	v_cmp_lt_i32_e32 vcc, v0, v42
	s_nop 1
	v_cndmask_b32_e32 v0, v235, v0, vcc
	v_lshlrev_b32_e32 v0, 2, v0
	ds_bpermute_b32 v44, v0, v34
	ds_bpermute_b32 v45, v0, v35
	ds_bpermute_b32 v42, v0, v36
	ds_bpermute_b32 v43, v0, v37
	ds_bpermute_b32 v46, v0, v38
	ds_bpermute_b32 v47, v0, v39
	ds_bpermute_b32 v48, v0, v40
	ds_bpermute_b32 v0, v0, v41
	s_and_saveexec_b64 s[4:5], s[8:9]
	s_cbranch_execz .LBB0_1036
	s_waitcnt lgkmcnt(0)
	v_mul_f32_e32 v51, v140, v0
	v_mov_b32_e32 v52, v41
	s_waitcnt vmcnt(3)
	v_mov_b32_e32 v53, v73
	v_mov_b32_e32 v50, v69
	v_mul_f32_e32 v48, v140, v48
	v_pk_mul_f32 v[50:51], v[52:53], v[50:51]
	v_pk_mul_f32 v[36:37], v[36:37], v[80:81]
	v_pk_mul_f32 v[34:35], v[34:35], v[78:79]
	v_pk_mul_f32 v[44:45], v[140:141], v[44:45] op_sel_hi:[0,1]
	v_pk_mul_f32 v[38:39], v[38:39], v[66:67]
	v_pk_mul_f32 v[46:47], v[140:141], v[46:47] op_sel_hi:[0,1]
	v_mul_f32_e32 v40, v40, v68
	v_mul_f32_e32 v48, v72, v48
	v_pk_mul_f32 v[42:43], v[140:141], v[42:43] op_sel_hi:[0,1]
	v_mov_b32_e32 v41, v50
	v_mov_b32_e32 v49, v51
	v_pk_fma_f32 v[34:35], v[74:75], v[44:45], v[34:35]
	v_pk_fma_f32 v[36:37], v[76:77], v[42:43], v[36:37]
	v_pk_fma_f32 v[38:39], v[70:71], v[46:47], v[38:39]
	v_pk_add_f32 v[40:41], v[40:41], v[48:49]

.LBB0_1116:
	v_and_b32_e32 v26, 64, v235
	v_xor_b32_e32 v0, 16, v235
	v_add_u32_e32 v26, 64, v26
	v_cmp_lt_i32_e32 vcc, v0, v26
	s_nop 1
	v_cndmask_b32_e32 v0, v235, v0, vcc
	v_lshlrev_b32_e32 v0, 2, v0
	ds_bpermute_b32 v28, v0, v18
	ds_bpermute_b32 v29, v0, v19
	ds_bpermute_b32 v26, v0, v20
	ds_bpermute_b32 v27, v0, v21
	ds_bpermute_b32 v30, v0, v22
	ds_bpermute_b32 v31, v0, v23
	ds_bpermute_b32 v32, v0, v24
	ds_bpermute_b32 v0, v0, v25
	s_and_saveexec_b64 s[4:5], s[8:9]
	s_cbranch_execz .LBB0_1118
	s_waitcnt lgkmcnt(0)
	v_mul_f32_e32 v32, v140, v32
	s_waitcnt vmcnt(9)
	v_mul_f32_e32 v32, v104, v32
	v_mul_f32_e32 v35, v140, v0
	v_mov_b32_e32 v104, v25
	v_mov_b32_e32 v34, v101
	v_pk_mul_f32 v[34:35], v[104:105], v[34:35]
	v_pk_mul_f32 v[20:21], v[20:21], v[112:113]
	v_pk_mul_f32 v[18:19], v[18:19], v[110:111]
	v_pk_mul_f32 v[28:29], v[140:141], v[28:29] op_sel_hi:[0,1]
	v_pk_mul_f32 v[22:23], v[22:23], v[98:99]
	v_pk_mul_f32 v[30:31], v[140:141], v[30:31] op_sel_hi:[0,1]
	v_mul_f32_e32 v24, v24, v100
	v_pk_mul_f32 v[26:27], v[140:141], v[26:27] op_sel_hi:[0,1]
	v_mov_b32_e32 v25, v34
	v_mov_b32_e32 v33, v35
	v_pk_fma_f32 v[18:19], v[106:107], v[28:29], v[18:19]
	v_pk_fma_f32 v[20:21], v[108:109], v[26:27], v[20:21]
	v_pk_fma_f32 v[22:23], v[102:103], v[30:31], v[22:23]
	v_pk_add_f32 v[24:25], v[24:25], v[32:33]

.LBB0_1156:
	v_and_b32_e32 v18, 64, v235
	v_xor_b32_e32 v0, 16, v235
	v_add_u32_e32 v18, 64, v18
	v_cmp_lt_i32_e32 vcc, v0, v18
	s_nop 1
	v_cndmask_b32_e32 v0, v235, v0, vcc
	v_lshlrev_b32_e32 v0, 2, v0
	ds_bpermute_b32 v20, v0, v10
	ds_bpermute_b32 v21, v0, v11
	ds_bpermute_b32 v18, v0, v12
	ds_bpermute_b32 v19, v0, v13
	ds_bpermute_b32 v22, v0, v14
	ds_bpermute_b32 v23, v0, v15
	ds_bpermute_b32 v24, v0, v16
	ds_bpermute_b32 v0, v0, v17
	s_and_saveexec_b64 s[4:5], s[8:9]
	s_cbranch_execz .LBB0_1158
	s_waitcnt lgkmcnt(0)
	v_mul_f32_e32 v24, v140, v24
	s_waitcnt vmcnt(6)
	v_mul_f32_e32 v24, v88, v24
	v_mul_f32_e32 v27, v140, v0
	v_mov_b32_e32 v88, v17
	v_mov_b32_e32 v26, v85
	v_pk_mul_f32 v[26:27], v[88:89], v[26:27]
	v_pk_mul_f32 v[12:13], v[12:13], v[96:97]
	v_pk_mul_f32 v[10:11], v[10:11], v[94:95]
	v_pk_mul_f32 v[20:21], v[140:141], v[20:21] op_sel_hi:[0,1]
	v_pk_mul_f32 v[14:15], v[14:15], v[82:83]
	v_pk_mul_f32 v[22:23], v[140:141], v[22:23] op_sel_hi:[0,1]
	v_mul_f32_e32 v16, v16, v84
	v_pk_mul_f32 v[18:19], v[140:141], v[18:19] op_sel_hi:[0,1]
	v_mov_b32_e32 v17, v26
	v_mov_b32_e32 v25, v27
	v_pk_fma_f32 v[10:11], v[90:91], v[20:21], v[10:11]
	v_pk_fma_f32 v[12:13], v[92:93], v[18:19], v[12:13]
	v_pk_fma_f32 v[14:15], v[86:87], v[22:23], v[14:15]
	v_pk_add_f32 v[16:17], v[16:17], v[24:25]

.LBB0_1196:
	v_and_b32_e32 v10, 64, v235
	v_xor_b32_e32 v0, 16, v235
	v_add_u32_e32 v10, 64, v10
	v_cmp_lt_i32_e32 vcc, v0, v10
	s_nop 1
	v_cndmask_b32_e32 v0, v235, v0, vcc
	v_lshlrev_b32_e32 v0, 2, v0
	ds_bpermute_b32 v12, v0, v2
	ds_bpermute_b32 v13, v0, v3
	ds_bpermute_b32 v10, v0, v4
	ds_bpermute_b32 v11, v0, v5
	ds_bpermute_b32 v14, v0, v6
	ds_bpermute_b32 v15, v0, v7
	ds_bpermute_b32 v16, v0, v8
	ds_bpermute_b32 v0, v0, v9
	s_and_saveexec_b64 s[4:5], s[8:9]
	s_cbranch_execz .LBB0_1198
	s_waitcnt lgkmcnt(0)
	v_mul_f32_e32 v16, v140, v16
	s_waitcnt vmcnt(3)
	v_mul_f32_e32 v16, v72, v16
	v_mul_f32_e32 v19, v140, v0
	v_mov_b32_e32 v72, v9
	v_mov_b32_e32 v18, v69
	v_pk_mul_f32 v[18:19], v[72:73], v[18:19]
	v_pk_mul_f32 v[4:5], v[4:5], v[80:81]
	v_pk_mul_f32 v[2:3], v[2:3], v[78:79]
	v_pk_mul_f32 v[12:13], v[140:141], v[12:13] op_sel_hi:[0,1]
	v_pk_mul_f32 v[6:7], v[6:7], v[66:67]
	v_pk_mul_f32 v[14:15], v[140:141], v[14:15] op_sel_hi:[0,1]
	v_mul_f32_e32 v8, v8, v68
	v_pk_mul_f32 v[10:11], v[140:141], v[10:11] op_sel_hi:[0,1]
	v_mov_b32_e32 v9, v18
	v_mov_b32_e32 v17, v19
	v_pk_fma_f32 v[2:3], v[74:75], v[12:13], v[2:3]
	v_pk_fma_f32 v[4:5], v[76:77], v[10:11], v[4:5]
	v_pk_fma_f32 v[6:7], v[70:71], v[14:15], v[6:7]
	v_pk_add_f32 v[8:9], v[8:9], v[16:17]
